# instruction selection in the VALU-bound attention loops: 31 canonicalising v_max(x,x) folded into the following v_max(0,.) and 3 in-place +0 adds dropped (wait states re-checked per site)
# baseline (speedup 1.0000x reference)
; DI void sb_item(const Params& p, int item, int lane) {
;     ...
;   const int w = item & 3, hd = (item >> 2) & 7, qb = (item >> 5) & 63, b = item >> 11;
;   const int tq = 128 * qb + 32 * w + l31;
;   const int token = b * SEQ + tq;
;   bf16x8 qf[4];
; #pragma unroll
;   for (int s = 0; s < 4; ++s) qf[s] = ldg8(proj + (size_t)token * INC + 768 + hd * 64 + 16 * s + 8 * h);
;   f32x16 oacc[2];
; #pragma unroll
;   for (int dt = 0; dt < 2; ++dt)
; #pragma unroll
;     for (int r = 0; r < 16; ++r) oacc[dt][r] = 0.f;
;   float carry = 0.f;
;   const int ktd = 4 * qb + w;
;   const bf16_t* kbase = proj + (size_t)(b * SEQ + l31) * INC + 1280 + hd * 64 + 8 * h;
;   const bf16_t* vbase = vbt + ((size_t)(b * 8 + hd) * 64 + l31) * SEQ + 8 * h;
;   bf16x8 kc[4], vc[4], kn[4], vn[4];
; #pragma unroll
;   for (int s = 0; s < 4; ++s) kc[s] = ldg8(kbase + (size_t)(32 * ktd) * INC + 16 * s);
; #pragma unroll
;   for (int s2 = 0; s2 < 2; ++s2)
; #pragma unroll
;     for (int dt = 0; dt < 2; ++dt) vc[2 * s2 + dt] = ldg8(vbase + (size_t)(32 * dt) * SEQ + 32 * ktd + 16 * s2);
;     ...
;     const int key0 = 32 * kt;
;     {
;       const int kp = kt > 0 ? kt - 1 : 0;
; #pragma unroll
;       for (int s = 0; s < 4; ++s) kn[s] = ldg8(kbase + (size_t)(32 * kp) * INC + 16 * s);
; #pragma unroll
;       for (int s2 = 0; s2 < 2; ++s2)
; #pragma unroll
;         for (int dt = 0; dt < 2; ++dt) vn[2 * s2 + dt] = ldg8(vbase + (size_t)(32 * dt) * SEQ + 32 * kp + 16 * s2);
;     }
;     f32x16 z;
; #pragma unroll
;     for (int r = 0; r < 16; ++r) z[r] = 0.f;
; #pragma unroll
;     for (int s = 0; s < 4; ++s) z = MFMA32(kc[s], qf[s], z);
;     const bool diag = (kt == ktd);
;     float T[4], P[4];
;     f32x16 lsg;
; #pragma unroll
;     for (int g = 0; g < 4; ++g) {
;       float l[4];
; #pragma unroll
;       for (int q = 0; q < 4; ++q) {
;         const int r = 4 * g + q;
;         const float zz = z[r];
;         const float sp = fmaxf(zz, 0.f) + lg2(1.f + ex2(-fabsf(zz)));
;         const bool causal = (!diag) || (key0 + crow(r, h) < tq);
;         l[q] = causal ? -sp : 0.f;
;         lsg[r] = causal ? (zz - sp) : -INFINITY;
;       }
;       z[4 * g + 3] = 0.f;
;       z[4 * g + 2] = l[3];
;       z[4 * g + 1] = l[3] + l[2];
;       z[4 * g + 0] = l[3] + l[2] + l[1];
;       T[g] = z[4 * g + 0] + l[0];
;     }
; #pragma unroll
;     for (int g = 0; g < 4; ++g) P[g] = xor32_get(T[g], h);
.LBB0_250:
	s_andn2_saveexec_b64 s[66:67], s[42:43]
	s_cbranch_execz .LBB0_245
	v_ashrrev_i32_e32 v2, 11, v83
	v_lshlrev_b32_e32 v1, 13, v2
	v_bfe_u32 v100, v83, 2, 3
	v_lshl_or_b32 v30, v0, 7, v138
	v_lshl_or_b32 v91, v0, 2, v137
	v_or_b32_e32 v0, v1, v119
	v_mov_b64_e32 v[4:5], s[48:49]
	v_or_b32_e32 v92, v30, v1
	v_mad_i64_i32 v[0:1], s[0:1], v0, s22, v[4:5]
	v_lshlrev_b32_e32 v80, 7, v100
	v_lshl_add_u64 v[0:1], v[0:1], 0, v[80:81]
	v_mov_b32_e32 v89, v81
	v_lshl_add_u64 v[94:95], v[0:1], 0, v[88:89]
	v_lshl_or_b32 v0, v2, 3, v100
	v_ashrrev_i32_e32 v1, 31, v0
	v_lshlrev_b64 v[0:1], 20, v[0:1]
	v_lshl_add_u64 v[96:97], v[86:87], 0, v[0:1]
	v_lshlrev_b32_e32 v0, 6, v91
	v_mov_b32_e32 v1, v81
	v_lshl_add_u64 v[0:1], v[96:97], 0, v[0:1]
	v_add_co_u32_e32 v2, vcc, s23, v0
	global_load_dwordx4 v[16:19], v[0:1], off
	s_nop 0
	v_addc_co_u32_e32 v3, vcc, 0, v1, vcc
	global_load_dwordx4 v[40:43], v[2:3], off
	global_load_dwordx4 v[36:39], v[0:1], off offset:32
	global_load_dwordx4 v[32:35], v[2:3], off offset:32
	v_mul_u32_u24_e32 v0, 0x12000, v91
	v_mad_i64_i32 v[4:5], s[0:1], v92, s22, v[4:5]
	v_lshlrev_b32_e32 v0, 1, v0
	v_mov_b32_e32 v1, v81
	v_lshl_add_u64 v[4:5], v[4:5], 0, v[80:81]
	v_lshl_add_u64 v[0:1], v[94:95], 0, v[0:1]
	v_lshl_add_u64 v[4:5], v[4:5], 0, v[88:89]
	global_load_dwordx4 v[20:23], v[0:1], off offset:2656
	global_load_dwordx4 v[24:27], v[0:1], off offset:2624
	global_load_dwordx4 v[44:47], v[0:1], off offset:2592
	s_nop 0
	global_load_dwordx4 v[0:3], v[0:1], off offset:2560
	s_nop 0
	global_load_dwordx4 v[48:51], v[4:5], off offset:1632
	global_load_dwordx4 v[52:55], v[4:5], off offset:1600
	global_load_dwordx4 v[56:59], v[4:5], off offset:1568
	global_load_dwordx4 v[60:63], v[4:5], off offset:1536
	s_waitcnt vmcnt(0)
	v_mfma_f32_32x32x16_bf16 v[0:15], v[0:3], v[60:63], 0
	v_mfma_f32_32x32x16_bf16 v[0:15], v[44:47], v[56:59], v[0:15]
	v_lshl_or_b32 v44, v91, 5, v82
	v_cmp_lt_u32_e32 vcc, v44, v30
	v_mfma_f32_32x32x16_bf16 v[0:15], v[24:27], v[52:55], v[0:15]
	v_mfma_f32_32x32x16_bf16 v[0:15], v[20:23], v[48:51], v[0:15]
	s_nop 11
	v_exp_f32_e64 v21, -|v0|
	v_max_f32_e32 v20, 0, v0
	v_add_f32_e32 v21, 1.0, v21
	v_log_f32_e32 v21, v21
	s_nop 0
	v_add_f32_e32 v20, v20, v21
	v_cndmask_b32_e64 v21, 0, -v20, vcc
	v_sub_f32_e32 v0, v0, v20
	v_exp_f32_e64 v20, -|v1|
	v_cndmask_b32_e32 v31, v142, v0, vcc
	v_max_f32_e32 v0, 0, v1
	v_add_f32_e32 v20, 1.0, v20
	v_log_f32_e32 v20, v20
	s_nop 0
	v_add_f32_e32 v0, v0, v20
	v_or_b32_e32 v20, 1, v44
	v_cmp_lt_u32_e32 vcc, v20, v30
	s_nop 1
	v_cndmask_b32_e64 v20, 0, -v0, vcc
	v_sub_f32_e32 v0, v1, v0
	v_exp_f32_e64 v1, -|v2|
	v_cndmask_b32_e32 v45, v142, v0, vcc
	v_max_f32_e32 v0, 0, v2
	v_add_f32_e32 v1, 1.0, v1
	v_log_f32_e32 v1, v1
	s_nop 0
	v_add_f32_e32 v0, v0, v1
	v_or_b32_e32 v1, 2, v44
	v_cmp_lt_u32_e32 vcc, v1, v30
	s_nop 1
	v_cndmask_b32_e64 v1, 0, -v0, vcc
	v_sub_f32_e32 v0, v2, v0
	v_exp_f32_e64 v2, -|v3|
	v_cndmask_b32_e32 v46, v142, v0, vcc
	v_max_f32_e32 v0, 0, v3
	v_add_f32_e32 v2, 1.0, v2
	v_log_f32_e32 v2, v2
	s_nop 0
	v_add_f32_e32 v0, v0, v2
	v_or_b32_e32 v2, 3, v44
	v_cmp_lt_u32_e32 vcc, v2, v30
	v_max_f32_e32 v2, v4, v4
	v_max_f32_e32 v2, 0, v2
	v_cndmask_b32_e64 v47, 0, -v0, vcc
	v_sub_f32_e32 v0, v3, v0
	v_exp_f32_e64 v3, -|v4|
	v_add_f32_e32 v65, v47, v1
	v_or_b32_e32 v1, 8, v44
	v_cndmask_b32_e32 v64, v142, v0, vcc
	v_add_f32_e32 v3, 1.0, v3
	v_log_f32_e32 v3, v3
	v_cmp_lt_u32_e32 vcc, v1, v30
	v_add_f32_e32 v66, v20, v65
	v_add_f32_e32 v0, v21, v66
	v_add_f32_e32 v3, v2, v3
	v_sub_f32_e32 v1, v4, v3
	v_cndmask_b32_e32 v4, v142, v1, vcc
	v_max_f32_e32 v26, 0, v5
	v_exp_f32_e64 v1, -|v5|
	v_cndmask_b32_e64 v2, 0, -v3, vcc
	v_exp_f32_e64 v3, -|v7|
	v_add_f32_e32 v1, 1.0, v1
	v_log_f32_e32 v28, v1
	v_max_f32_e32 v20, 0, v6
	v_exp_f32_e64 v1, -|v6|
	v_add_f32_e32 v3, 1.0, v3
	v_log_f32_e32 v3, v3
	v_add_f32_e32 v1, 1.0, v1
	v_log_f32_e32 v22, v1
	v_max_f32_e32 v1, 0, v7
	v_add_f32_e32 v1, v1, v3
	v_or_b32_e32 v3, 11, v44
	v_cmp_lt_u32_e32 vcc, v3, v30
	v_exp_f32_e64 v3, -|v10|
	s_nop 0
	v_cndmask_b32_e64 v24, 0, -v1, vcc
	v_sub_f32_e32 v1, v7, v1
	v_cndmask_b32_e32 v7, v142, v1, vcc
	v_max_f32_e32 v27, 0, v8
	v_exp_f32_e64 v1, -|v8|
	v_add_f32_e32 v3, 1.0, v3
	v_log_f32_e32 v3, v3
	v_add_f32_e32 v1, 1.0, v1
	v_log_f32_e32 v29, v1
	v_max_f32_e32 v21, 0, v9
	v_exp_f32_e64 v1, -|v9|
	s_nop 0
	v_add_f32_e32 v1, 1.0, v1
	v_log_f32_e32 v23, v1
	v_max_f32_e32 v1, 0, v10
	v_add_f32_e32 v1, v1, v3
	v_or_b32_e32 v3, 18, v44
	v_cmp_lt_u32_e32 vcc, v3, v30
	v_pk_add_f32 v[20:21], v[20:21], v[22:23]
	s_nop 0
	v_cndmask_b32_e64 v3, 0, -v1, vcc
	v_sub_f32_e32 v1, v10, v1
	v_exp_f32_e64 v10, -|v11|
	v_cndmask_b32_e32 v67, v142, v1, vcc
	v_max_f32_e32 v1, 0, v11
	v_add_f32_e32 v10, 1.0, v10
	v_log_f32_e32 v10, v10
	s_nop 0
	v_add_f32_e32 v1, v1, v10
	v_or_b32_e32 v10, 19, v44
	v_cmp_lt_u32_e32 vcc, v10, v30
	v_exp_f32_e64 v10, -|v12|
	s_nop 0
	v_cndmask_b32_e64 v68, 0, -v1, vcc
	v_add_f32_e32 v25, v68, v3
	v_add_f32_e32 v10, 1.0, v10
	v_log_f32_e32 v10, v10
	v_max_f32_e32 v3, 0, v12
	v_sub_f32_e32 v1, v11, v1
	v_add_f32_e32 v3, v3, v10
	v_exp_f32_e64 v10, -|v13|
	v_cndmask_b32_e32 v69, v142, v1, vcc
	v_or_b32_e32 v1, 24, v44
	v_cmp_lt_u32_e32 vcc, v1, v30
	v_add_f32_e32 v10, 1.0, v10
	v_log_f32_e32 v10, v10
	v_exp_f32_e64 v11, -|v14|
	v_cndmask_b32_e64 v1, 0, -v3, vcc
	v_sub_f32_e32 v3, v12, v3
	v_cndmask_b32_e32 v70, v142, v3, vcc
	v_max_f32_e32 v3, 0, v13
	v_add_f32_e32 v3, v3, v10
	v_or_b32_e32 v10, 25, v44
	v_add_f32_e32 v11, 1.0, v11
	v_cmp_lt_u32_e32 vcc, v10, v30
	v_log_f32_e32 v11, v11
	v_exp_f32_e64 v12, -|v15|
	v_cndmask_b32_e64 v10, 0, -v3, vcc
	v_sub_f32_e32 v3, v13, v3
; #define MFMA32(a, b, c) __builtin_amdgcn_mfma_f32_32x32x16_bf16((a), (b), (c), 0, 0, 0)
; DI float xor32_get(float x, int h) { auto r = __builtin_amdgcn_permlane32_swap(__float_as_uint(x), __float_as_uint(x), false, false); return __uint_as_float(h ? r[0] : r[1]); }
; DI float ex2(float x) { return __builtin_amdgcn_exp2f(x); }
; DI void sb_item(const Params& p, int item, int lane) {
;     ...
;     for (int g = 0; g < 4; ++g) P[g] = xor32_get(T[g], h);
;     float tp[4], after[4];
; #pragma unroll
;     for (int g = 0; g < 4; ++g) tp[g] = T[g] + P[g];
;     after[3] = 0.f; after[2] = tp[3]; after[1] = tp[3] + tp[2]; after[0] = after[1] + tp[1];
;     const float total = after[0] + tp[0];
;     f32x16 a;
; #pragma unroll
;     for (int g = 0; g < 4; ++g) {
;       const float base = carry + after[g] + (h == 0 ? P[g] : 0.f);
; #pragma unroll
;       for (int q = 0; q < 4; ++q) a[4 * g + q] = ex2(lsg[4 * g + q] + base + z[4 * g + q]);
;     }
;     carry += total;
; #pragma unroll
;     for (int s2 = 0; s2 < 2; ++s2) {
;       bf16x8 pb = packp(a, s2);
; #pragma unroll
;       for (int dt = 0; dt < 2; ++dt) oacc[dt] = MFMA32(vc[2 * s2 + dt], pb, oacc[dt]);
;     }
;     if (__all(carry < -151.f)) break;
; #pragma unroll
;     for (int s = 0; s < 4; ++s) { kc[s] = kn[s]; vc[s] = vn[s]; }
	v_cndmask_b32_e32 v71, v142, v3, vcc
	v_max_f32_e32 v3, 0, v14
	v_add_f32_e32 v3, v3, v11
	v_or_b32_e32 v11, 26, v44
	v_add_f32_e32 v12, 1.0, v12
	v_cmp_lt_u32_e32 vcc, v11, v30
	v_log_f32_e32 v12, v12
	s_nop 0
	v_cndmask_b32_e64 v11, 0, -v3, vcc
	v_sub_f32_e32 v3, v14, v3
	v_cndmask_b32_e32 v72, v142, v3, vcc
	v_max_f32_e32 v3, 0, v15
	v_add_f32_e32 v3, v3, v12
	v_or_b32_e32 v12, 27, v44
	v_cmp_lt_u32_e32 vcc, v12, v30
	s_nop 1
	v_cndmask_b32_e64 v73, 0, -v3, vcc
	v_sub_f32_e32 v3, v15, v3
	v_add_f32_e32 v75, v73, v11
	v_cndmask_b32_e32 v74, v142, v3, vcc
	v_add_f32_e32 v76, v10, v75
	v_mov_b32_e32 v3, v0
	v_mov_b32_e32 v10, v0
	v_add_f32_e32 v1, v1, v76
	s_nop 0
	v_permlane32_swap_b32_e32 v3, v10
	v_cndmask_b32_e64 v10, v3, v10, s[38:39]
	v_mov_b32_e32 v3, v1
	v_mov_b32_e32 v11, v1
	s_nop 1
	v_permlane32_swap_b32_e32 v3, v11
	v_cndmask_b32_e64 v77, v3, v11, s[38:39]
	v_pk_add_f32 v[14:15], v[26:27], v[28:29]
	v_add_f32_e32 v13, v1, v77
	v_sub_f32_e32 v1, v5, v14
	v_or_b32_e32 v5, 9, v44
	v_or_b32_e32 v3, 16, v44
	v_cmp_lt_u32_e64 s[0:1], v5, v30
	v_cmp_lt_u32_e32 vcc, v3, v30
	v_or_b32_e32 v3, 17, v44
	v_cndmask_b32_e64 v5, v142, v1, s[0:1]
	v_sub_f32_e32 v1, v6, v20
	v_or_b32_e32 v6, 10, v44
	v_cmp_lt_u32_e64 s[40:41], v3, v30
	v_cmp_lt_u32_e64 s[42:43], v6, v30
	v_cndmask_b32_e64 v23, 0, -v15, vcc
	v_cndmask_b32_e64 v22, 0, -v14, s[0:1]
	v_cndmask_b32_e64 v6, v142, v1, s[42:43]
	v_sub_f32_e32 v1, v8, v15
	v_cndmask_b32_e64 v15, 0, -v21, s[40:41]
	v_cndmask_b32_e64 v14, 0, -v20, s[42:43]
	v_cndmask_b32_e32 v26, v142, v1, vcc
	v_sub_f32_e32 v1, v9, v21
	v_pk_add_f32 v[8:9], v[14:15], v[24:25]
	v_cndmask_b32_e64 v27, v142, v1, s[40:41]
	v_pk_add_f32 v[14:15], v[22:23], v[8:9]
	s_nop 0
	v_mov_b32_e32 v1, v15
	v_mov_b32_e32 v3, v15
	s_nop 1
	v_permlane32_swap_b32_e32 v1, v3
	v_cndmask_b32_e64 v3, v1, v3, s[38:39]
	v_pk_add_f32 v[20:21], v[2:3], v[14:15]
	v_cndmask_b32_e64 v3, 0, v3, s[38:39]
	v_mov_b32_e32 v1, v20
	v_mov_b32_e32 v2, v20
	s_nop 1
	v_permlane32_swap_b32_e32 v1, v2
	v_cndmask_b32_e64 v12, v1, v2, s[38:39]
	v_pk_add_f32 v[20:21], v[20:21], v[12:13]
	v_cndmask_b32_e64 v12, 0, v12, s[38:39]
	v_mov_b32_e32 v1, v20
	v_add_f32_e32 v20, 0, v21
	v_add_f32_e32 v12, v12, v20
	v_add_f32_e32 v5, v5, v12
	v_mov_b32_e32 v11, v21
	v_add_f32_e32 v5, v8, v5
	v_add_f32_e32 v8, 0, v13
	v_pk_add_f32 v[0:1], v[0:1], v[10:11]
	v_add_f32_e32 v3, v3, v8
	v_add_f32_e32 v2, 0, v1
	v_cndmask_b32_e64 v10, 0, v10, s[38:39]
	v_add_f32_e32 v8, v26, v3
	v_add_f32_e32 v2, v10, v2
	v_add_f32_e32 v8, v9, v8
	v_add_f32_e32 v11, v45, v2
	v_exp_f32_e32 v45, v8
	v_add_f32_e32 v8, v27, v3
	v_add_f32_e32 v8, v25, v8
	v_add_f32_e32 v15, v46, v2
	v_exp_f32_e32 v46, v8
	v_add_f32_e32 v8, v67, v3
	v_add_f32_e32 v3, v69, v3
	v_add_f32_e32 v10, v31, v2
	v_add_f32_e32 v2, v64, v2
	v_exp_f32_e32 v64, v3
	v_add_f32_e32 v3, 0, v77
	v_add_f32_e32 v4, v4, v12
	v_add_f32_e32 v6, v6, v12
	v_add_f32_e32 v8, v68, v8
	v_cndmask_b32_e64 v3, 0, v3, s[38:39]
	v_add_f32_e32 v10, v66, v10
	v_add_f32_e32 v11, v65, v11
	v_add_f32_e32 v15, v47, v15
	v_add_f32_e32 v4, v14, v4
	v_add_f32_e32 v6, v24, v6
	v_add_f32_e32 v7, v7, v12
	v_exp_f32_e32 v47, v8
	v_add_f32_e32 v8, v70, v3
	v_exp_f32_e32 v10, v10
	v_exp_f32_e32 v11, v11
	v_exp_f32_e32 v15, v15
	v_exp_f32_e32 v2, v2
	v_exp_f32_e32 v4, v4
	v_exp_f32_e32 v5, v5
	v_exp_f32_e32 v6, v6
	v_exp_f32_e32 v7, v7
	v_add_f32_e32 v8, v76, v8
	v_exp_f32_e32 v65, v8
	v_add_f32_e32 v8, v71, v3
	v_add_f32_e32 v8, v75, v8
	v_exp_f32_e32 v66, v8
	v_add_f32_e32 v8, v72, v3
	v_add_f32_e32 v3, v74, v3
	v_add_f32_e32 v8, v73, v8
	v_exp_f32_e32 v68, v3
	v_add_f32_e32 v44, v0, v1
	v_cvt_pk_bf16_f32 v0, v10, v11
	v_cvt_pk_bf16_f32 v1, v15, v2
	v_cvt_pk_bf16_f32 v2, v4, v5
	v_cvt_pk_bf16_f32 v3, v6, v7
	v_exp_f32_e32 v67, v8
	v_cmp_gt_f32_e32 vcc, s25, v44
	v_mfma_f32_32x32x16_bf16 v[16:31], v[16:19], v[0:3], 0
	s_cmp_lg_u64 vcc, exec
	s_cselect_b64 s[0:1], -1, 0
	v_cmp_ne_u32_e32 vcc, 0, v91
	s_and_b64 s[18:19], vcc, s[0:1]
	v_mfma_f32_32x32x16_bf16 v[0:15], v[40:43], v[0:3], 0
	v_cvt_pk_bf16_f32 v40, v45, v46
	v_cvt_pk_bf16_f32 v41, v47, v64
	v_cvt_pk_bf16_f32 v42, v65, v66
	v_cvt_pk_bf16_f32 v43, v67, v68
	s_nop 1
	v_mfma_f32_32x32x16_bf16 v[16:31], v[36:39], v[40:43], v[16:31]
	v_mfma_f32_32x32x16_bf16 v[0:15], v[32:35], v[40:43], v[0:15]
	s_and_saveexec_b64 s[0:1], s[18:19]
	s_cbranch_execz .LBB0_255
	v_lshrrev_b32_e32 v32, 3, v83
	v_and_b32_e32 v32, 0xfc, v32
	v_add_lshl_u32 v80, v139, v32, 5
	v_add_f32_e32 v89, 0, v44
	s_mov_b64 s[18:19], 0
; #define MFMA32(a, b, c) __builtin_amdgcn_mfma_f32_32x32x16_bf16((a), (b), (c), 0, 0, 0)
; DI void sb_item(const Params& p, int item, int lane) {
;     ...
;     const int key0 = 32 * kt;
;     {
;       const int kp = kt > 0 ? kt - 1 : 0;
; #pragma unroll
;       for (int s = 0; s < 4; ++s) kn[s] = ldg8(kbase + (size_t)(32 * kp) * INC + 16 * s);
; #pragma unroll
;       for (int s2 = 0; s2 < 2; ++s2)
; #pragma unroll
;         for (int dt = 0; dt < 2; ++dt) vn[2 * s2 + dt] = ldg8(vbase + (size_t)(32 * dt) * SEQ + 32 * kp + 16 * s2);
;     }
;     f32x16 z;
; #pragma unroll
;     for (int r = 0; r < 16; ++r) z[r] = 0.f;
; #pragma unroll
;     for (int s = 0; s < 4; ++s) z = MFMA32(kc[s], qf[s], z);
.LBB0_253:
	v_lshl_add_u64 v[32:33], v[80:81], 1, v[96:97]
	v_add_co_u32_e32 v34, vcc, 0x80000, v32
	v_mad_u64_u32 v[36:37], s[26:27], v80, s22, v[94:95]
	s_nop 0
	v_addc_co_u32_e32 v35, vcc, 0, v33, vcc
	global_load_dwordx4 v[76:79], v[32:33], off
	global_load_dwordx4 v[72:75], v[34:35], off
	global_load_dwordx4 v[64:67], v[32:33], off offset:32
	global_load_dwordx4 v[68:71], v[34:35], off offset:32
	s_nop 0
	global_load_dwordx4 v[32:35], v[36:37], off offset:2560
	global_load_dwordx4 v[102:105], v[36:37], off offset:2592
	global_load_dwordx4 v[106:109], v[36:37], off offset:2624
	global_load_dwordx4 v[110:113], v[36:37], off offset:2656
	v_add_u32_e32 v93, -1, v91
	v_subrev_u32_e32 v80, 32, v80
	s_waitcnt vmcnt(3)
	v_mfma_f32_32x32x16_bf16 v[32:47], v[32:35], v[60:63], 0
	s_waitcnt vmcnt(2)
	v_mfma_f32_32x32x16_bf16 v[32:47], v[102:105], v[56:59], v[32:47]
	s_waitcnt vmcnt(1)
	v_mfma_f32_32x32x16_bf16 v[32:47], v[106:109], v[52:55], v[32:47]
	s_waitcnt vmcnt(0)
; #define MFMA32(a, b, c) __builtin_amdgcn_mfma_f32_32x32x16_bf16((a), (b), (c), 0, 0, 0)
; DI int crow(int r, int h) { return (r & 3) + 8 * (r >> 2) + 4 * h; }
; DI float xor32_get(float x, int h) { auto r = __builtin_amdgcn_permlane32_swap(__float_as_uint(x), __float_as_uint(x), false, false); return __uint_as_float(h ? r[0] : r[1]); }
; DI float ex2(float x) { return __builtin_amdgcn_exp2f(x); }
; DI float lg2(float x) { return __builtin_amdgcn_logf(x); }
; DI void sb_item(const Params& p, int item, int lane) {
;     ...
;     const bool diag = (kt == ktd);
;     float T[4], P[4];
;     f32x16 lsg;
; #pragma unroll
;     for (int g = 0; g < 4; ++g) {
;       float l[4];
; #pragma unroll
;       for (int q = 0; q < 4; ++q) {
;         const int r = 4 * g + q;
;         const float zz = z[r];
;         const float sp = fmaxf(zz, 0.f) + lg2(1.f + ex2(-fabsf(zz)));
;         const bool causal = (!diag) || (key0 + crow(r, h) < tq);
;         l[q] = causal ? -sp : 0.f;
;         lsg[r] = causal ? (zz - sp) : -INFINITY;
;       }
;       z[4 * g + 3] = 0.f;
;       z[4 * g + 2] = l[3];
;       z[4 * g + 1] = l[3] + l[2];
;       z[4 * g + 0] = l[3] + l[2] + l[1];
;       T[g] = z[4 * g + 0] + l[0];
;     }
; #pragma unroll
;     for (int g = 0; g < 4; ++g) P[g] = xor32_get(T[g], h);
;     float tp[4], after[4];
; #pragma unroll
;     for (int g = 0; g < 4; ++g) tp[g] = T[g] + P[g];
;     after[3] = 0.f; after[2] = tp[3]; after[1] = tp[3] + tp[2]; after[0] = after[1] + tp[1];
;     const float total = after[0] + tp[0];
;     f32x16 a;
; #pragma unroll
;     for (int g = 0; g < 4; ++g) {
;       const float base = carry + after[g] + (h == 0 ? P[g] : 0.f);
; #pragma unroll
;       for (int q = 0; q < 4; ++q) a[4 * g + q] = ex2(lsg[4 * g + q] + base + z[4 * g + q]);
;     }
;     carry += total;
; #pragma unroll
;     for (int s2 = 0; s2 < 2; ++s2) {
;       bf16x8 pb = packp(a, s2);
; #pragma unroll
;       for (int dt = 0; dt < 2; ++dt) oacc[dt] = MFMA32(vc[2 * s2 + dt], pb, oacc[dt]);
;     }
;     if (__all(carry < -151.f)) break;
; #pragma unroll
;     for (int s = 0; s < 4; ++s) { kc[s] = kn[s]; vc[s] = vn[s]; }
	v_mfma_f32_32x32x16_bf16 v[32:47], v[110:113], v[48:51], v[32:47]
	s_nop 11
	v_exp_f32_e64 v101, -|v34|
	v_max_f32_e32 v99, 0, v34
	v_mov_b32_e32 v117, v37
	v_add_f32_e32 v101, 1.0, v101
	v_log_f32_e32 v101, v101
	v_mov_b32_e32 v145, v41
	v_max_f32_e32 v102, 0, v32
	v_add_f32_e32 v99, v99, v101
	v_xor_b32_e32 v108, 0x80000000, v99
	v_sub_f32_e32 v143, v34, v99
	v_exp_f32_e64 v99, -|v35|
	v_max_f32_e32 v34, 0, v35
	v_exp_f32_e64 v98, -|v32|
	v_add_f32_e32 v99, 1.0, v99
	v_log_f32_e32 v99, v99
	v_add_f32_e32 v98, 1.0, v98
	v_log_f32_e32 v104, v98
	v_add_f32_e32 v110, v34, v99
	v_sub_f32_e32 v150, v35, v110
	v_exp_f32_e64 v35, -|v36|
	v_max_f32_e32 v34, 0, v36
	v_exp_f32_e64 v99, -|v38|
	v_add_f32_e32 v35, 1.0, v35
	v_log_f32_e32 v35, v35
	v_add_f32_e32 v99, 1.0, v99
	v_log_f32_e32 v99, v99
	v_add_f32_e32 v35, v34, v35
	v_max_f32_e32 v113, 0, v37
	v_exp_f32_e64 v34, -|v37|
	v_max_f32_e32 v106, 0, v33
	v_exp_f32_e64 v98, -|v33|
	v_add_f32_e32 v34, 1.0, v34
	v_log_f32_e32 v115, v34
	v_max_f32_e32 v34, 0, v38
	v_add_f32_e32 v34, v34, v99
	v_xor_b32_e32 v116, 0x80000000, v34
	v_sub_f32_e32 v151, v38, v34
	v_max_f32_e32 v112, 0, v39
	v_exp_f32_e64 v34, -|v39|
	v_add_f32_e32 v98, 1.0, v98
	v_log_f32_e32 v98, v98
	v_add_f32_e32 v34, 1.0, v34
	v_log_f32_e32 v114, v34
	s_nop 0
	v_pk_add_f32 v[112:113], v[112:113], v[114:115]
	s_nop 0
	v_pk_add_f32 v[114:115], v[116:117], v[112:113] neg_lo:[0,1] neg_hi:[0,1]
	v_sub_f32_e32 v152, v39, v112
	v_mov_b32_e32 v38, v114
	v_mov_b32_e32 v39, v36
	v_mov_b32_e32 v34, v113
	v_pk_add_f32 v[116:117], v[38:39], v[34:35] neg_lo:[0,1] neg_hi:[0,1]
	v_sub_f32_e32 v103, v116, v35
	v_exp_f32_e64 v35, -|v40|
	v_max_f32_e32 v34, 0, v40
	v_exp_f32_e64 v36, -|v42|
	v_add_f32_e32 v35, 1.0, v35
	v_log_f32_e32 v35, v35
	v_add_f32_e32 v36, 1.0, v36
	v_log_f32_e32 v36, v36
	v_add_f32_e32 v35, v34, v35
	v_max_f32_e32 v37, 0, v41
	v_exp_f32_e64 v34, -|v41|
	s_nop 0
	v_add_f32_e32 v34, 1.0, v34
	v_log_f32_e32 v39, v34
	v_max_f32_e32 v34, 0, v42
	v_add_f32_e32 v34, v34, v36
	v_xor_b32_e32 v144, 0x80000000, v34
	v_sub_f32_e32 v113, v42, v34
	v_max_f32_e32 v36, 0, v43
	v_exp_f32_e64 v34, -|v43|
	s_nop 0
	v_add_f32_e32 v34, 1.0, v34
	v_log_f32_e32 v38, v34
	s_nop 0
	v_pk_add_f32 v[146:147], v[36:37], v[38:39]
	s_nop 0
	v_pk_add_f32 v[144:145], v[144:145], v[146:147] neg_lo:[0,1] neg_hi:[0,1]
	v_mov_b32_e32 v37, v40
	v_mov_b32_e32 v36, v144
	v_mov_b32_e32 v34, v147
	v_pk_add_f32 v[148:149], v[36:37], v[34:35] neg_lo:[0,1] neg_hi:[0,1]
	v_sub_f32_e32 v111, v148, v35
	v_exp_f32_e64 v35, -|v44|
	v_max_f32_e32 v34, 0, v44
	v_exp_f32_e64 v36, -|v46|
	v_mov_b32_e32 v39, v45
	v_add_f32_e32 v35, 1.0, v35
	v_log_f32_e32 v35, v35
	v_add_f32_e32 v36, 1.0, v36
	v_log_f32_e32 v36, v36
	v_sub_f32_e32 v153, v43, v146
	v_add_f32_e32 v41, v34, v35
	v_max_f32_e32 v35, 0, v45
	v_exp_f32_e64 v34, -|v45|
	s_nop 0
	v_add_f32_e32 v34, 1.0, v34
	v_log_f32_e32 v37, v34
	v_max_f32_e32 v34, 0, v46
	v_add_f32_e32 v34, v34, v36
	v_exp_f32_e64 v36, -|v47|
	v_xor_b32_e32 v38, 0x80000000, v34
	v_sub_f32_e32 v101, v46, v34
	v_add_f32_e32 v36, 1.0, v36
	v_log_f32_e32 v36, v36
	v_max_f32_e32 v34, 0, v47
	v_pk_add_f32 v[34:35], v[34:35], v[36:37]
	s_nop 0
	v_pk_add_f32 v[36:37], v[38:39], v[34:35] neg_lo:[0,1] neg_hi:[0,1]
	v_mov_b32_e32 v39, v44
	v_mov_b32_e32 v38, v36
	v_mov_b32_e32 v40, v35
	v_pk_add_f32 v[38:39], v[38:39], v[40:41] neg_lo:[0,1] neg_hi:[0,1]
	v_mov_b32_e32 v35, v103
	v_mov_b32_e32 v40, v103
	s_nop 1
	v_permlane32_swap_b32_e32 v35, v40
	v_cndmask_b32_e64 v105, v35, v40, s[38:39]
	v_mov_b32_e32 v35, v111
	v_mov_b32_e32 v40, v111
	v_sub_f32_e32 v107, v38, v41
	s_nop 0
	v_permlane32_swap_b32_e32 v35, v40
	v_cndmask_b32_e64 v109, v35, v40, s[38:39]
	v_mov_b32_e32 v35, v107
	v_mov_b32_e32 v40, v107
	s_nop 1
	v_permlane32_swap_b32_e32 v35, v40
	v_cndmask_b32_e64 v99, v35, v40, s[38:39]
	v_pk_add_f32 v[40:41], v[102:103], v[104:105]
	v_pk_add_f32 v[106:107], v[106:107], v[98:99]
	v_sub_f32_e32 v35, v32, v40
	v_sub_f32_e32 v44, v33, v106
	v_pk_add_f32 v[32:33], v[108:109], v[110:111] neg_lo:[0,1] neg_hi:[0,1]
	v_pk_add_f32 v[42:43], v[108:109], v[110:111]
	v_sub_f32_e32 v33, v32, v106
	v_pk_add_f32 v[42:43], v[42:43], v[106:107]
	v_sub_f32_e32 v40, v33, v40
	v_mov_b32_e32 v42, v40
	v_mov_b32_e32 v45, v40
	s_nop 1
	v_permlane32_swap_b32_e32 v42, v45
	v_cndmask_b32_e64 v42, v42, v45, s[38:39]
	v_add_f32_e32 v46, v43, v41
	v_add_f32_e32 v45, v40, v42
	v_add_f32_e32 v40, v89, v46
	v_cndmask_b32_e64 v41, 0, v42, s[38:39]
	v_add_f32_e32 v40, v41, v40
	v_add_f32_e32 v35, v35, v40
	v_add_f32_e32 v33, v33, v35
	v_exp_f32_e32 v98, v33
	v_add_f32_e32 v33, v44, v40
	v_add_f32_e32 v32, v32, v33
	v_exp_f32_e32 v102, v32
	v_add_f32_e32 v32, v143, v40
	v_sub_f32_e32 v32, v32, v110
	v_exp_f32_e32 v103, v32
	v_add_f32_e32 v32, v150, v40
	v_exp_f32_e32 v104, v32
	v_add_f32_e32 v32, v89, v43
	v_cndmask_b32_e64 v33, 0, v105, s[38:39]
	v_add_f32_e32 v32, v33, v32
	v_add_f32_e32 v33, v117, v32
	v_add_f32_e32 v33, v116, v33
	v_exp_f32_e32 v41, v33
	v_add_f32_e32 v33, v115, v32
	v_add_f32_e32 v33, v114, v33
	v_exp_f32_e32 v42, v33
	v_add_f32_e32 v33, v151, v32
	v_add_f32_e32 v32, v152, v32
	v_sub_f32_e32 v33, v33, v112
	v_add_f32_e32 v105, 0, v89
	v_cndmask_b32_e64 v99, 0, v99, s[38:39]
	v_exp_f32_e32 v43, v33
	v_exp_f32_e32 v44, v32
	v_add_f32_e32 v99, v105, v99
	v_add_f32_e32 v37, v37, v99
	v_add_f32_e32 v39, v39, v99
	v_add_f32_e32 v36, v36, v37
	v_add_f32_e32 v38, v38, v39
	v_exp_f32_e32 v106, v36
	v_add_f32_e32 v36, v101, v99
	v_sub_f32_e32 v47, v47, v34
	v_add_f32_e32 v32, v89, v107
	v_cndmask_b32_e64 v33, 0, v109, s[38:39]
	v_exp_f32_e32 v105, v38
	v_sub_f32_e32 v34, v36, v34
	v_cvt_pk_bf16_f32 v36, v98, v102
	v_cvt_pk_bf16_f32 v37, v103, v104
	v_cvt_pk_bf16_f32 v38, v41, v42
	v_cvt_pk_bf16_f32 v39, v43, v44
	v_add_f32_e32 v40, v33, v32
	v_add_f32_e32 v32, v149, v40
	v_mfma_f32_32x32x16_bf16 v[16:31], v[76:79], v[36:39], v[16:31]
	v_add_f32_e32 v33, v145, v40
	v_add_f32_e32 v35, v113, v40
	v_add_f32_e32 v40, v153, v40
	v_add_f32_e32 v32, v148, v32
	v_add_f32_e32 v33, v144, v33
	v_sub_f32_e32 v35, v35, v146
	v_mfma_f32_32x32x16_bf16 v[0:15], v[72:75], v[36:39], v[0:15]
	v_exp_f32_e32 v101, v34
	v_add_f32_e32 v34, v47, v99
	v_exp_f32_e32 v32, v32
	v_exp_f32_e32 v33, v33
	v_exp_f32_e32 v35, v35
	v_exp_f32_e32 v40, v40
	v_exp_f32_e32 v47, v34
	v_cvt_pk_bf16_f32 v32, v32, v33
	v_cvt_pk_bf16_f32 v34, v105, v106
	v_cvt_pk_bf16_f32 v33, v35, v40
	v_cvt_pk_bf16_f32 v35, v101, v47
	v_add_f32_e32 v45, v45, v46
	v_add_f32_e32 v89, v89, v45
	v_mfma_f32_32x32x16_bf16 v[16:31], v[64:67], v[32:35], v[16:31]
	v_cmp_gt_f32_e32 vcc, s25, v89
	s_cmp_eq_u64 vcc, exec
	s_cselect_b64 s[26:27], -1, 0
	v_cmp_gt_u32_e32 vcc, 2, v91
	s_or_b64 s[26:27], s[26:27], vcc
	s_and_b64 s[26:27], exec, s[26:27]
	s_or_b64 s[18:19], s[26:27], s[18:19]
	v_mfma_f32_32x32x16_bf16 v[0:15], v[68:71], v[32:35], v[0:15]
	v_mov_b32_e32 v91, v93
	s_andn2_b64 exec, exec, s[18:19]
	s_cbranch_execnz .LBB0_253
	s_or_b64 exec, exec, s[18:19]
